# move down-weight f32->bf16 conversion jobs of layers 1-3 from gate-up shadow slots to the prologue (shadow slots overran their slack)
# speedup vs baseline: 1.0094x; 1.0094x over previous
.LBB0_457:
	s_andn2_b64 vcc, exec, s[22:23]
	s_movk_i32 s48, 0x400
	s_cbranch_vccnz .LBB0_459
	s_branch .LBB0_442
	s_add_i32 s20, s43, -8
	s_lshr_b32 s8, s20, 1
	s_and_b32 s9, s43, 1
	s_cmp_eq_u32 s9, 0
	s_cselect_b32 s2, 64, 0x50
	s_add_u32 s2, s80, s2
	s_addc_u32 s3, s81, 0
	s_load_dwordx2 s[2:3], s[2:3], 0x0
	s_mul_i32 s22, s8, 0xb00000
	s_mul_hi_u32 s21, s8, 0xb00000
	s_mov_b32 s24, 0
	s_waitcnt lgkmcnt(0)
	s_mov_b64 s[44:45], 0
	s_add_u32 s46, s2, s22
	s_addc_u32 s47, s3, s21
	s_mul_hi_u32 s2, s20, 0x580000
	s_mul_i32 s20, s20, 0x580000
	s_add_u32 s20, s34, s20
	s_addc_u32 s21, s35, s2
	s_mov_b64 s[2:3], -1
	s_movk_i32 s88, 0x400
	s_movk_i32 s48, 0xb00

.LBB0_549:
	s_andn2_b64 vcc, exec, s[22:23]
	s_movk_i32 s49, 0x400
	s_cbranch_vccnz .LBB0_551
	s_branch .LBB0_534
	s_add_i32 s20, s48, -8
	s_lshr_b32 s8, s20, 1
	s_and_b32 s9, s48, 1
	s_cmp_eq_u32 s9, 0
	s_cselect_b32 s2, 64, 0x50
	s_add_u32 s2, s80, s2
	s_addc_u32 s3, s81, 0
	s_load_dwordx2 s[2:3], s[2:3], 0x0
	s_mul_i32 s22, s8, 0xb00000
	s_mul_hi_u32 s21, s8, 0xb00000
	s_mov_b32 s24, 0
	s_waitcnt lgkmcnt(0)
	s_mov_b64 s[44:45], 0
	s_add_u32 s46, s2, s22
	s_addc_u32 s47, s3, s21
	s_mul_hi_u32 s2, s20, 0x580000
	s_mul_i32 s20, s20, 0x580000
	s_add_u32 s20, s35, s20
	s_addc_u32 s21, s36, s2
	s_mov_b64 s[2:3], -1
	s_movk_i32 s88, 0x400
	s_movk_i32 s49, 0xb00

.LBB0_614:
	s_andn2_b64 vcc, exec, s[14:15]
	s_movk_i32 s31, 0x400
	s_cbranch_vccnz .LBB0_616
	s_add_i32 s12, s30, -8
	s_lshr_b32 s8, s12, 1
	s_bitcmp0_b32 s30, 0
	s_cselect_b32 s2, 64, 0x50
	s_add_u32 s2, s80, s2
	s_addc_u32 s3, s81, 0
	s_load_dwordx2 s[2:3], s[2:3], 0x0
	s_mul_i32 s15, s8, 0xb00000
	s_mul_hi_u32 s14, s8, 0xb00000
	s_mul_hi_u32 s13, s12, 0x580000
	s_mul_i32 s12, s12, 0x580000
	s_waitcnt lgkmcnt(0)
	s_add_u32 s46, s2, s15
	s_addc_u32 s47, s3, s14
	s_add_u32 s12, s24, s12
	s_mov_b32 s9, 0
	s_addc_u32 s13, s25, s13
	s_mov_b64 s[44:45], 0
	s_mov_b64 s[2:3], -1
	s_movk_i32 s88, 0x400
	s_movk_i32 s31, 0xb00
	s_branch .LBB0_618
